# attention phase: one static s_setprio 1 for waves 4-7 (younger half), reset at phase exit; on top of packed-softmax version
# speedup vs baseline: 1.0039x; 1.0039x over previous
; #define LAS __attribute__((address_space(3)))
; __global__ void __launch_bounds__(512) mega(Params p) {
;     ...
;   { LAS unsigned* qslot = (LAS unsigned*)(lds + 2 * ATT_BUF + 2 * 1536);
;     for (;;) { if (threadIdx.x == 0) qslot[0] = atomicAdd(ctr, 1u); __syncthreads(); const unsigned it = qslot[0]; __syncthreads(); if (it >= 2112u) break;
;       int item; if (it < 64u) item = 2048 + (int)it; else if (it < 64u + 1792u) { const int j = (int)it - 64, b = j / 224, r = j - b * 224; item = (b << 8) | ((8 + (r >> 2)) << 2) | (r & 3); }
;       else { const int j = (int)it - 1856, cc = 7 - (j >> 5), r = j & 31; item = ((r >> 2) << 8) | (cc << 2) | (r & 3); }
;       attn_wg_item(p, item, lds); } }
.LBB0_790:
	v_readfirstlane_b32 s100, v148
	s_nop 1
	s_bitcmp1_b32 s100, 8
	s_cbranch_scc0 .Lattn_noprio
	s_setprio 1

; __device__ __forceinline__ void xcd_barrier(const XcdBarrier& b) {
;     asm volatile("s_waitcnt vmcnt(0)" ::: "memory");
;     __syncthreads();
;     if (threadIdx.x == 0) {
;         unsigned* bar = b.bar;
;         __builtin_amdgcn_s_waitcnt(0);
;         unsigned nloc = b.st[0], nx = b.st[1];
;         if (nloc == 0u) { xcd_barrier_complete(bar, b.x, nloc, nx); b.st[0] = nloc; b.st[1] = nx; }
; __global__ void __launch_bounds__(512) mega(Params p) {
;     ...
;     for (;;) { if (threadIdx.x == 0) qslot[0] = atomicAdd(ctr, 1u); __syncthreads(); const unsigned it = qslot[0]; __syncthreads(); if (it >= 2112u) break;
;       int item; if (it < 64u) item = 2048 + (int)it; else if (it < 64u + 1792u) { const int j = (int)it - 64, b = j / 224, r = j - b * 224; item = (b << 8) | ((8 + (r >> 2)) << 2) | (r & 3); }
;       else { const int j = (int)it - 1856, cc = 7 - (j >> 5), r = j & 31; item = ((r >> 2) << 8) | (cc << 2) | (r & 3); }
;       attn_wg_item(p, item, lds); } }
;   xcd_barrier(xbar);
.LBB0_829:
	s_setprio 0
	s_waitcnt vmcnt(0)
	s_waitcnt lgkmcnt(0)
	s_barrier
	s_and_saveexec_b64 s[0:1], s[92:93]
	s_cbranch_execz .LBB0_881
	s_add_i32 s2, 0, 0x24ff0
	v_mov_b32_e32 v0, s2
	s_waitcnt vmcnt(0) expcnt(0) lgkmcnt(0)
	ds_read_b32 v2, v0
	s_add_i32 s2, 0, 0x24ff4
	v_mov_b32_e32 v0, s2
	ds_read_b32 v0, v0
	s_waitcnt lgkmcnt(1)
	v_cmp_ne_u32_e32 vcc, 0, v2
	s_cbranch_vccnz .LBB0_845
	s_add_u32 s4, s88, 0x1000
	s_addc_u32 s5, s89, 0
	s_add_u32 s6, s88, 0x1100
	s_addc_u32 s7, s89, 0
	s_add_u32 s8, s88, 0x1200
	v_readlane_b32 s2, v247, 0
	s_addc_u32 s9, s89, 0
	s_mul_i32 s2, s91, s2
	s_add_u32 s10, s88, 0x1300
	s_mul_i32 s2, s2, s90
	s_addc_u32 s11, s89, 0
	s_mov_b32 s3, 1
	v_mov_b32_e32 v16, 0
	s_branch .LBB0_833
